# swiglu epilogue: static prio 1 for the leading wave half so it reaches the next K-loop first
# speedup vs baseline: 1.0097x; 1.0097x over previous
; #define LAS __attribute__((address_space(3)))
; __device__ __forceinline__ unsigned pk2(float lo, float hi) { f32x2 v = {lo, hi}; bf16x2_t b = __builtin_convertvector(v, bf16x2_t); return __builtin_bit_cast(unsigned, b); }
; __device__ __forceinline__ void epi_swiglu(bf16_t* H, const LAS float* tbl, const f32x4 (&acc)[2][2][4][2], const Unit& u, int wr, int wc, int fr, int fq) {
;     const int col0 = u.pn * 128 + wc * 32 + fq * 8;
; #pragma unroll
;     for (int it = 0; it < 8; ++it) {
;         const int ai = it >> 2, m = it & 3; const int r = opaque(EPI_ROW(it));
;         const float rs = tbl[EPI_LROW(it)];
;         u32x4 w;
; #pragma unroll
;         for (int n = 0; n < 2; ++n) {
;             const f32x4 g = acc[ai][0][m][n] * rs, up = acc[ai][1][m][n] * rs; float hv[4];
; #pragma unroll
;             for (int i = 0; i < 4; ++i) hv[i] = g[i] * __builtin_amdgcn_rcpf(1.0f + __expf(-g[i])) * up[i];
;             w[2 * n] = pk2(hv[0], hv[1]); w[2 * n + 1] = pk2(hv[2], hv[3]);
;         }
;         *(u32x4*)(H + ((size_t)(r >> 8) * (DFF / 64) + (col0 >> 6)) * 16384 + (r & 255) * 64 + (col0 & 63)) = w;
;     }
; }
.LBB0_752:
	s_and_b64 vcc, exec, s[2:3]
	s_cbranch_vccz .LBB0_754
	s_mov_b64 s[2:3], s[96:97]
	s_add_u32 s2, s2, 0x17e00000
	s_addc_u32 s3, s3, 0
	s_lshl_b32 s12, s77, 7
	v_readlane_b32 s13, v255, 1
	s_or_b32 s12, s12, s13
	v_readlane_b32 s13, v254, 31
	s_lshl_b32 s13, s13, 2
	s_add_i32 s39, s39, s13
	s_lshl_b32 s14, s81, 8
	s_waitcnt lgkmcnt(0)
	v_add_u32_e32 v131, s14, v193
	v_readlane_b32 s14, v254, 34
	v_readlane_b32 s15, v254, 35
	s_and_b64 vcc, exec, s[14:15]
	s_cbranch_vccz .Lsw_noprio
	s_setprio 1
.Lsw_noprio:
	v_lshl_add_u32 v130, v183, 2, s39
	ds_read_b32 v140, v130
	ds_read_b32 v141, v130 offset:64
	ds_read_b32 v142, v130 offset:128
	ds_read_b32 v143, v130 offset:192
	ds_read_b32 v144, v130 offset:512
	ds_read_b32 v145, v130 offset:576
	ds_read_b32 v146, v130 offset:640
	ds_read_b32 v147, v130 offset:704
	s_ashr_i32 s12, s12, 6
	s_ashr_i32 s13, s12, 31
	v_mov_b32_e32 v199, v0
	v_lshrrev_b32_e32 v132, 8, v131
	v_mul_i32_i24_e32 v132, 0x58, v132
	v_ashrrev_i32_e32 v133, 31, v132
	v_lshl_add_u64 v[132:133], v[132:133], 0, s[12:13]
	v_lshlrev_b64 v[132:133], 15, v[132:133]
	v_lshl_add_u64 v[132:133], s[2:3], 0, v[132:133]
	v_lshlrev_b32_e32 v134, 7, v131
	v_and_b32_e32 v134, 0x7f80, v134
	v_mov_b32_e32 v135, v0
	v_lshl_add_u64 v[132:133], v[132:133], 0, v[134:135]
	v_lshl_add_u64 v[132:133], v[132:133], 0, v[198:199]
	s_mov_b64 s[12:13], 0x1000
	s_mov_b64 s[14:15], 0x5000
	v_lshl_add_u64 v[134:135], v[132:133], 0, s[12:13]
	v_lshl_add_u64 v[136:137], v[132:133], 0, s[14:15]
	v_mov_b32_e32 v138, 1.0
	v_mov_b32_e32 v139, 1.0
	s_waitcnt lgkmcnt(0)
	v_mul_f32_e32 v148, 0xbfb8aa3b, v140
	v_mul_f32_e32 v150, v140, v140
	v_rcp_f32_e32 v150, v150
	v_pk_mul_f32 v[152:153], v[126:127], v[148:149] op_sel_hi:[1,0]
	v_pk_mul_f32 v[154:155], v[128:129], v[148:149] op_sel_hi:[1,0]
	v_pk_mul_f32 v[156:157], v[118:119], v[148:149] op_sel_hi:[1,0]
	v_pk_mul_f32 v[158:159], v[120:121], v[148:149] op_sel_hi:[1,0]
	v_exp_f32_e32 v152, v152
	v_exp_f32_e32 v153, v153
	v_exp_f32_e32 v154, v154
	v_exp_f32_e32 v155, v155
	v_exp_f32_e32 v156, v156
	v_exp_f32_e32 v157, v157
	v_exp_f32_e32 v158, v158
	v_exp_f32_e32 v159, v159
	v_pk_mul_f32 v[126:127], v[126:127], v[122:123]
	v_pk_mul_f32 v[128:129], v[128:129], v[124:125]
	v_pk_mul_f32 v[118:119], v[118:119], v[114:115]
	v_pk_mul_f32 v[120:121], v[120:121], v[116:117]
	v_pk_fma_f32 v[152:153], v[152:153], v[150:151], v[150:151] op_sel_hi:[1,0,0]
	v_pk_fma_f32 v[154:155], v[154:155], v[150:151], v[150:151] op_sel_hi:[1,0,0]
	v_pk_fma_f32 v[156:157], v[156:157], v[150:151], v[150:151] op_sel_hi:[1,0,0]
	v_pk_fma_f32 v[158:159], v[158:159], v[150:151], v[150:151] op_sel_hi:[1,0,0]
	v_rcp_f32_e32 v152, v152
	v_rcp_f32_e32 v153, v153
	v_rcp_f32_e32 v154, v154
	v_rcp_f32_e32 v155, v155
	v_rcp_f32_e32 v156, v156
	v_rcp_f32_e32 v157, v157
	v_rcp_f32_e32 v158, v158
	v_rcp_f32_e32 v159, v159
	v_pk_mul_f32 v[126:127], v[126:127], v[152:153]
	v_pk_mul_f32 v[128:129], v[128:129], v[154:155]
	v_pk_mul_f32 v[118:119], v[118:119], v[156:157]
	v_pk_mul_f32 v[120:121], v[120:121], v[158:159]
	v_cvt_pk_bf16_f32 v160, v126, v127
	v_cvt_pk_bf16_f32 v161, v128, v129
	v_cvt_pk_bf16_f32 v162, v118, v119
	v_cvt_pk_bf16_f32 v163, v120, v121
	global_store_dwordx4 v[134:135], v[160:163], off offset:-4096
	v_mul_f32_e32 v148, 0xbfb8aa3b, v141
	v_mul_f32_e32 v150, v141, v141
	v_rcp_f32_e32 v150, v150
	v_pk_mul_f32 v[152:153], v[110:111], v[148:149] op_sel_hi:[1,0]
	v_pk_mul_f32 v[154:155], v[112:113], v[148:149] op_sel_hi:[1,0]
	v_pk_mul_f32 v[156:157], v[102:103], v[148:149] op_sel_hi:[1,0]
	v_pk_mul_f32 v[158:159], v[104:105], v[148:149] op_sel_hi:[1,0]
	v_exp_f32_e32 v152, v152
	v_exp_f32_e32 v153, v153
	v_exp_f32_e32 v154, v154
	v_exp_f32_e32 v155, v155
	v_exp_f32_e32 v156, v156
	v_exp_f32_e32 v157, v157
	v_exp_f32_e32 v158, v158
	v_exp_f32_e32 v159, v159
	v_pk_mul_f32 v[110:111], v[110:111], v[106:107]
	v_pk_mul_f32 v[112:113], v[112:113], v[108:109]
	v_pk_mul_f32 v[102:103], v[102:103], v[98:99]
	v_pk_mul_f32 v[104:105], v[104:105], v[100:101]
	v_pk_fma_f32 v[152:153], v[152:153], v[150:151], v[150:151] op_sel_hi:[1,0,0]
	v_pk_fma_f32 v[154:155], v[154:155], v[150:151], v[150:151] op_sel_hi:[1,0,0]
	v_pk_fma_f32 v[156:157], v[156:157], v[150:151], v[150:151] op_sel_hi:[1,0,0]
	v_pk_fma_f32 v[158:159], v[158:159], v[150:151], v[150:151] op_sel_hi:[1,0,0]
	v_rcp_f32_e32 v152, v152
	v_rcp_f32_e32 v153, v153
	v_rcp_f32_e32 v154, v154
	v_rcp_f32_e32 v155, v155
	v_rcp_f32_e32 v156, v156
	v_rcp_f32_e32 v157, v157
	v_rcp_f32_e32 v158, v158
	v_rcp_f32_e32 v159, v159
	v_pk_mul_f32 v[110:111], v[110:111], v[152:153]
	v_pk_mul_f32 v[112:113], v[112:113], v[154:155]
	v_pk_mul_f32 v[102:103], v[102:103], v[156:157]
	v_pk_mul_f32 v[104:105], v[104:105], v[158:159]
	v_cvt_pk_bf16_f32 v164, v110, v111
	v_cvt_pk_bf16_f32 v165, v112, v113
	v_cvt_pk_bf16_f32 v166, v102, v103
	v_cvt_pk_bf16_f32 v167, v104, v105
	global_store_dwordx4 v[134:135], v[164:167], off offset:-2048
	v_mul_f32_e32 v148, 0xbfb8aa3b, v142
	v_mul_f32_e32 v150, v142, v142
	v_rcp_f32_e32 v150, v150
	v_pk_mul_f32 v[152:153], v[94:95], v[148:149] op_sel_hi:[1,0]
	v_pk_mul_f32 v[154:155], v[96:97], v[148:149] op_sel_hi:[1,0]
	v_pk_mul_f32 v[156:157], v[86:87], v[148:149] op_sel_hi:[1,0]
	v_pk_mul_f32 v[158:159], v[88:89], v[148:149] op_sel_hi:[1,0]
	v_exp_f32_e32 v152, v152
	v_exp_f32_e32 v153, v153
	v_exp_f32_e32 v154, v154
	v_exp_f32_e32 v155, v155
	v_exp_f32_e32 v156, v156
	v_exp_f32_e32 v157, v157
	v_exp_f32_e32 v158, v158
	v_exp_f32_e32 v159, v159
	v_pk_mul_f32 v[94:95], v[94:95], v[90:91]
	v_pk_mul_f32 v[96:97], v[96:97], v[92:93]
	v_pk_mul_f32 v[86:87], v[86:87], v[82:83]
; __device__ __forceinline__ unsigned pk2(float lo, float hi) { f32x2 v = {lo, hi}; bf16x2_t b = __builtin_convertvector(v, bf16x2_t); return __builtin_bit_cast(unsigned, b); }
; __device__ __forceinline__ void epi_swiglu(bf16_t* H, const LAS float* tbl, const f32x4 (&acc)[2][2][4][2], const Unit& u, int wr, int wc, int fr, int fq) {
;     ...
;     for (int it = 0; it < 8; ++it) {
;         const int ai = it >> 2, m = it & 3; const int r = opaque(EPI_ROW(it));
;         const float rs = tbl[EPI_LROW(it)];
;         u32x4 w;
; #pragma unroll
;         for (int n = 0; n < 2; ++n) {
;             const f32x4 g = acc[ai][0][m][n] * rs, up = acc[ai][1][m][n] * rs; float hv[4];
; #pragma unroll
;             for (int i = 0; i < 4; ++i) hv[i] = g[i] * __builtin_amdgcn_rcpf(1.0f + __expf(-g[i])) * up[i];
;             w[2 * n] = pk2(hv[0], hv[1]); w[2 * n + 1] = pk2(hv[2], hv[3]);
;         }
;         *(u32x4*)(H + ((size_t)(r >> 8) * (DFF / 64) + (col0 >> 6)) * 16384 + (r & 255) * 64 + (col0 & 63)) = w;
;     }
	v_pk_mul_f32 v[88:89], v[88:89], v[84:85]
	v_pk_fma_f32 v[152:153], v[152:153], v[150:151], v[150:151] op_sel_hi:[1,0,0]
	v_pk_fma_f32 v[154:155], v[154:155], v[150:151], v[150:151] op_sel_hi:[1,0,0]
	v_pk_fma_f32 v[156:157], v[156:157], v[150:151], v[150:151] op_sel_hi:[1,0,0]
	v_pk_fma_f32 v[158:159], v[158:159], v[150:151], v[150:151] op_sel_hi:[1,0,0]
	v_rcp_f32_e32 v152, v152
	v_rcp_f32_e32 v153, v153
	v_rcp_f32_e32 v154, v154
	v_rcp_f32_e32 v155, v155
	v_rcp_f32_e32 v156, v156
	v_rcp_f32_e32 v157, v157
	v_rcp_f32_e32 v158, v158
	v_rcp_f32_e32 v159, v159
	v_pk_mul_f32 v[94:95], v[94:95], v[152:153]
	v_pk_mul_f32 v[96:97], v[96:97], v[154:155]
	v_pk_mul_f32 v[86:87], v[86:87], v[156:157]
	v_pk_mul_f32 v[88:89], v[88:89], v[158:159]
	v_cvt_pk_bf16_f32 v160, v94, v95
	v_cvt_pk_bf16_f32 v161, v96, v97
	v_cvt_pk_bf16_f32 v162, v86, v87
	v_cvt_pk_bf16_f32 v163, v88, v89
	global_store_dwordx4 v[134:135], v[160:163], off
	v_mul_f32_e32 v148, 0xbfb8aa3b, v143
	v_mul_f32_e32 v150, v143, v143
	v_rcp_f32_e32 v150, v150
	v_pk_mul_f32 v[152:153], v[78:79], v[148:149] op_sel_hi:[1,0]
	v_pk_mul_f32 v[154:155], v[80:81], v[148:149] op_sel_hi:[1,0]
	v_pk_mul_f32 v[156:157], v[70:71], v[148:149] op_sel_hi:[1,0]
	v_pk_mul_f32 v[158:159], v[72:73], v[148:149] op_sel_hi:[1,0]
	v_exp_f32_e32 v152, v152
	v_exp_f32_e32 v153, v153
	v_exp_f32_e32 v154, v154
	v_exp_f32_e32 v155, v155
	v_exp_f32_e32 v156, v156
	v_exp_f32_e32 v157, v157
	v_exp_f32_e32 v158, v158
	v_exp_f32_e32 v159, v159
	v_pk_mul_f32 v[78:79], v[78:79], v[74:75]
	v_pk_mul_f32 v[80:81], v[80:81], v[76:77]
	v_pk_mul_f32 v[70:71], v[70:71], v[66:67]
	v_pk_mul_f32 v[72:73], v[72:73], v[68:69]
	v_pk_fma_f32 v[152:153], v[152:153], v[150:151], v[150:151] op_sel_hi:[1,0,0]
	v_pk_fma_f32 v[154:155], v[154:155], v[150:151], v[150:151] op_sel_hi:[1,0,0]
	v_pk_fma_f32 v[156:157], v[156:157], v[150:151], v[150:151] op_sel_hi:[1,0,0]
	v_pk_fma_f32 v[158:159], v[158:159], v[150:151], v[150:151] op_sel_hi:[1,0,0]
	v_rcp_f32_e32 v152, v152
	v_rcp_f32_e32 v153, v153
	v_rcp_f32_e32 v154, v154
	v_rcp_f32_e32 v155, v155
	v_rcp_f32_e32 v156, v156
	v_rcp_f32_e32 v157, v157
	v_rcp_f32_e32 v158, v158
	v_rcp_f32_e32 v159, v159
	v_pk_mul_f32 v[78:79], v[78:79], v[152:153]
	v_pk_mul_f32 v[80:81], v[80:81], v[154:155]
	v_pk_mul_f32 v[70:71], v[70:71], v[156:157]
	v_pk_mul_f32 v[72:73], v[72:73], v[158:159]
	v_cvt_pk_bf16_f32 v164, v78, v79
	v_cvt_pk_bf16_f32 v165, v80, v81
	v_cvt_pk_bf16_f32 v166, v70, v71
	v_cvt_pk_bf16_f32 v167, v72, v73
	global_store_dwordx4 v[134:135], v[164:167], off offset:2048
	v_mul_f32_e32 v148, 0xbfb8aa3b, v144
	v_mul_f32_e32 v150, v144, v144
	v_rcp_f32_e32 v150, v150
	v_pk_mul_f32 v[152:153], v[62:63], v[148:149] op_sel_hi:[1,0]
	v_pk_mul_f32 v[154:155], v[64:65], v[148:149] op_sel_hi:[1,0]
	v_pk_mul_f32 v[156:157], v[54:55], v[148:149] op_sel_hi:[1,0]
	v_pk_mul_f32 v[158:159], v[56:57], v[148:149] op_sel_hi:[1,0]
	v_exp_f32_e32 v152, v152
	v_exp_f32_e32 v153, v153
	v_exp_f32_e32 v154, v154
	v_exp_f32_e32 v155, v155
	v_exp_f32_e32 v156, v156
	v_exp_f32_e32 v157, v157
	v_exp_f32_e32 v158, v158
	v_exp_f32_e32 v159, v159
	v_pk_mul_f32 v[62:63], v[62:63], v[58:59]
	v_pk_mul_f32 v[64:65], v[64:65], v[60:61]
	v_pk_mul_f32 v[54:55], v[54:55], v[50:51]
	v_pk_mul_f32 v[56:57], v[56:57], v[52:53]
	v_pk_fma_f32 v[152:153], v[152:153], v[150:151], v[150:151] op_sel_hi:[1,0,0]
	v_pk_fma_f32 v[154:155], v[154:155], v[150:151], v[150:151] op_sel_hi:[1,0,0]
	v_pk_fma_f32 v[156:157], v[156:157], v[150:151], v[150:151] op_sel_hi:[1,0,0]
	v_pk_fma_f32 v[158:159], v[158:159], v[150:151], v[150:151] op_sel_hi:[1,0,0]
	v_rcp_f32_e32 v152, v152
	v_rcp_f32_e32 v153, v153
	v_rcp_f32_e32 v154, v154
	v_rcp_f32_e32 v155, v155
	v_rcp_f32_e32 v156, v156
	v_rcp_f32_e32 v157, v157
	v_rcp_f32_e32 v158, v158
	v_rcp_f32_e32 v159, v159
	v_pk_mul_f32 v[62:63], v[62:63], v[152:153]
	v_pk_mul_f32 v[64:65], v[64:65], v[154:155]
	v_pk_mul_f32 v[54:55], v[54:55], v[156:157]
	v_pk_mul_f32 v[56:57], v[56:57], v[158:159]
	v_cvt_pk_bf16_f32 v160, v62, v63
	v_cvt_pk_bf16_f32 v161, v64, v65
	v_cvt_pk_bf16_f32 v162, v54, v55
	v_cvt_pk_bf16_f32 v163, v56, v57
	global_store_dwordx4 v[136:137], v[160:163], off offset:-4096
	v_mul_f32_e32 v148, 0xbfb8aa3b, v145
	v_mul_f32_e32 v150, v145, v145
	v_rcp_f32_e32 v150, v150
	v_pk_mul_f32 v[152:153], v[46:47], v[148:149] op_sel_hi:[1,0]
	v_pk_mul_f32 v[154:155], v[48:49], v[148:149] op_sel_hi:[1,0]
	v_pk_mul_f32 v[156:157], v[38:39], v[148:149] op_sel_hi:[1,0]
	v_pk_mul_f32 v[158:159], v[40:41], v[148:149] op_sel_hi:[1,0]
; __device__ __forceinline__ unsigned pk2(float lo, float hi) { f32x2 v = {lo, hi}; bf16x2_t b = __builtin_convertvector(v, bf16x2_t); return __builtin_bit_cast(unsigned, b); }
; __device__ __forceinline__ void epi_swiglu(bf16_t* H, const LAS float* tbl, const f32x4 (&acc)[2][2][4][2], const Unit& u, int wr, int wc, int fr, int fq) {
;     ...
;     for (int it = 0; it < 8; ++it) {
;         const int ai = it >> 2, m = it & 3; const int r = opaque(EPI_ROW(it));
;         const float rs = tbl[EPI_LROW(it)];
;         u32x4 w;
; #pragma unroll
;         for (int n = 0; n < 2; ++n) {
;             const f32x4 g = acc[ai][0][m][n] * rs, up = acc[ai][1][m][n] * rs; float hv[4];
; #pragma unroll
;             for (int i = 0; i < 4; ++i) hv[i] = g[i] * __builtin_amdgcn_rcpf(1.0f + __expf(-g[i])) * up[i];
;             w[2 * n] = pk2(hv[0], hv[1]); w[2 * n + 1] = pk2(hv[2], hv[3]);
;         }
;         *(u32x4*)(H + ((size_t)(r >> 8) * (DFF / 64) + (col0 >> 6)) * 16384 + (r & 255) * 64 + (col0 & 63)) = w;
;     }
; }
	v_exp_f32_e32 v152, v152
	v_exp_f32_e32 v153, v153
	v_exp_f32_e32 v154, v154
	v_exp_f32_e32 v155, v155
	v_exp_f32_e32 v156, v156
	v_exp_f32_e32 v157, v157
	v_exp_f32_e32 v158, v158
	v_exp_f32_e32 v159, v159
	v_pk_mul_f32 v[46:47], v[46:47], v[42:43]
	v_pk_mul_f32 v[48:49], v[48:49], v[44:45]
	v_pk_mul_f32 v[38:39], v[38:39], v[34:35]
	v_pk_mul_f32 v[40:41], v[40:41], v[36:37]
	v_pk_fma_f32 v[152:153], v[152:153], v[150:151], v[150:151] op_sel_hi:[1,0,0]
	v_pk_fma_f32 v[154:155], v[154:155], v[150:151], v[150:151] op_sel_hi:[1,0,0]
	v_pk_fma_f32 v[156:157], v[156:157], v[150:151], v[150:151] op_sel_hi:[1,0,0]
	v_pk_fma_f32 v[158:159], v[158:159], v[150:151], v[150:151] op_sel_hi:[1,0,0]
	v_rcp_f32_e32 v152, v152
	v_rcp_f32_e32 v153, v153
	v_rcp_f32_e32 v154, v154
	v_rcp_f32_e32 v155, v155
	v_rcp_f32_e32 v156, v156
	v_rcp_f32_e32 v157, v157
	v_rcp_f32_e32 v158, v158
	v_rcp_f32_e32 v159, v159
	v_pk_mul_f32 v[46:47], v[46:47], v[152:153]
	v_pk_mul_f32 v[48:49], v[48:49], v[154:155]
	v_pk_mul_f32 v[38:39], v[38:39], v[156:157]
	v_pk_mul_f32 v[40:41], v[40:41], v[158:159]
	v_cvt_pk_bf16_f32 v164, v46, v47
	v_cvt_pk_bf16_f32 v165, v48, v49
	v_cvt_pk_bf16_f32 v166, v38, v39
	v_cvt_pk_bf16_f32 v167, v40, v41
	global_store_dwordx4 v[136:137], v[164:167], off offset:-2048
	v_mul_f32_e32 v148, 0xbfb8aa3b, v146
	v_mul_f32_e32 v150, v146, v146
	v_rcp_f32_e32 v150, v150
	v_pk_mul_f32 v[152:153], v[30:31], v[148:149] op_sel_hi:[1,0]
	v_pk_mul_f32 v[154:155], v[32:33], v[148:149] op_sel_hi:[1,0]
	v_pk_mul_f32 v[156:157], v[22:23], v[148:149] op_sel_hi:[1,0]
	v_pk_mul_f32 v[158:159], v[24:25], v[148:149] op_sel_hi:[1,0]
	v_exp_f32_e32 v152, v152
	v_exp_f32_e32 v153, v153
	v_exp_f32_e32 v154, v154
	v_exp_f32_e32 v155, v155
	v_exp_f32_e32 v156, v156
	v_exp_f32_e32 v157, v157
	v_exp_f32_e32 v158, v158
	v_exp_f32_e32 v159, v159
	v_pk_mul_f32 v[30:31], v[30:31], v[26:27]
	v_pk_mul_f32 v[32:33], v[32:33], v[28:29]
	v_pk_mul_f32 v[22:23], v[22:23], v[18:19]
	v_pk_mul_f32 v[24:25], v[24:25], v[20:21]
	v_pk_fma_f32 v[152:153], v[152:153], v[150:151], v[150:151] op_sel_hi:[1,0,0]
	v_pk_fma_f32 v[154:155], v[154:155], v[150:151], v[150:151] op_sel_hi:[1,0,0]
	v_pk_fma_f32 v[156:157], v[156:157], v[150:151], v[150:151] op_sel_hi:[1,0,0]
	v_pk_fma_f32 v[158:159], v[158:159], v[150:151], v[150:151] op_sel_hi:[1,0,0]
	v_rcp_f32_e32 v152, v152
	v_rcp_f32_e32 v153, v153
	v_rcp_f32_e32 v154, v154
	v_rcp_f32_e32 v155, v155
	v_rcp_f32_e32 v156, v156
	v_rcp_f32_e32 v157, v157
	v_rcp_f32_e32 v158, v158
	v_rcp_f32_e32 v159, v159
	v_pk_mul_f32 v[30:31], v[30:31], v[152:153]
	v_pk_mul_f32 v[32:33], v[32:33], v[154:155]
	v_pk_mul_f32 v[22:23], v[22:23], v[156:157]
	v_pk_mul_f32 v[24:25], v[24:25], v[158:159]
	v_cvt_pk_bf16_f32 v160, v30, v31
	v_cvt_pk_bf16_f32 v161, v32, v33
	v_cvt_pk_bf16_f32 v162, v22, v23
	v_cvt_pk_bf16_f32 v163, v24, v25
	global_store_dwordx4 v[136:137], v[160:163], off
	v_mul_f32_e32 v148, 0xbfb8aa3b, v147
	v_mul_f32_e32 v150, v147, v147
	v_rcp_f32_e32 v150, v150
	v_pk_mul_f32 v[152:153], v[14:15], v[148:149] op_sel_hi:[1,0]
	v_pk_mul_f32 v[154:155], v[16:17], v[148:149] op_sel_hi:[1,0]
	v_pk_mul_f32 v[156:157], v[6:7], v[148:149] op_sel_hi:[1,0]
	v_pk_mul_f32 v[158:159], v[8:9], v[148:149] op_sel_hi:[1,0]
	v_exp_f32_e32 v152, v152
	v_exp_f32_e32 v153, v153
	v_exp_f32_e32 v154, v154
	v_exp_f32_e32 v155, v155
	v_exp_f32_e32 v156, v156
	v_exp_f32_e32 v157, v157
	v_exp_f32_e32 v158, v158
	v_exp_f32_e32 v159, v159
	v_pk_mul_f32 v[14:15], v[14:15], v[10:11]
	v_pk_mul_f32 v[16:17], v[16:17], v[12:13]
	v_pk_mul_f32 v[6:7], v[6:7], v[2:3]
	v_pk_mul_f32 v[8:9], v[8:9], v[4:5]
	v_pk_fma_f32 v[152:153], v[152:153], v[150:151], v[150:151] op_sel_hi:[1,0,0]
	v_pk_fma_f32 v[154:155], v[154:155], v[150:151], v[150:151] op_sel_hi:[1,0,0]
	v_pk_fma_f32 v[156:157], v[156:157], v[150:151], v[150:151] op_sel_hi:[1,0,0]
	v_pk_fma_f32 v[158:159], v[158:159], v[150:151], v[150:151] op_sel_hi:[1,0,0]
	v_rcp_f32_e32 v152, v152
	v_rcp_f32_e32 v153, v153
	v_rcp_f32_e32 v154, v154
	v_rcp_f32_e32 v155, v155
	v_rcp_f32_e32 v156, v156
	v_rcp_f32_e32 v157, v157
	v_rcp_f32_e32 v158, v158
	v_rcp_f32_e32 v159, v159
	v_pk_mul_f32 v[14:15], v[14:15], v[152:153]
	v_pk_mul_f32 v[16:17], v[16:17], v[154:155]
	v_pk_mul_f32 v[6:7], v[6:7], v[156:157]
	v_pk_mul_f32 v[8:9], v[8:9], v[158:159]
	v_cvt_pk_bf16_f32 v164, v14, v15
	v_cvt_pk_bf16_f32 v165, v16, v17
	v_cvt_pk_bf16_f32 v166, v6, v7
	v_cvt_pk_bf16_f32 v167, v8, v9
	global_store_dwordx4 v[136:137], v[164:167], off offset:2048
	s_setprio 0
